# grid barrier: first counter barrier flat with per-XCD registration; XCD population and XCD count read back (no assumption on workgroup placement)
# speedup vs baseline: 1.0032x; 1.0032x over previous
; #define SEAM(k) do { if (IN(k) && IN((k) + 1)) grid.sync(); if (PROBE_PH >= 0) { const unsigned long long tn_ = __builtin_amdgcn_s_memrealtime(); if ((PROBE_PH >> (k)) & 1) tp1 += tn_ - tp0; tp0 = tn_; } } while (0)
; __global__ void __launch_bounds__(512, 2) mega(Params p) {
;     ...
;     SEAM(1);
.LBB0_284:
	s_cmp_gt_i32 s67, 2
	s_cselect_b64 s[2:3], -1, 0
	s_and_b64 s[0:1], s[0:1], s[2:3]
	s_andn2_b64 vcc, exec, s[0:1]
	s_cbranch_vccnz .LBB0_296
	v_and_b32_e32 v1, 0x3fffffff, v0
	v_cmp_eq_u32_e32 vcc, 0, v1
	s_waitcnt vmcnt(0) lgkmcnt(0)
	s_barrier
	s_and_saveexec_b64 s[0:1], vcc
	s_cbranch_execz .LBB0_295
	s_load_dwordx2 s[4:5], s[68:69], 0x58
	s_getreg_b32 s101, hwreg(HW_REG_XCC_ID)
	s_and_b32 s101, s101, 7
	s_lshr_b32 s98, s101, 1
	s_lshl_b32 s98, s98, 2
	s_and_b32 s99, s101, 1
	s_lshl_b32 s99, s99, 4
	v_mov_b32_e32 v3, s98
	v_mov_b32_e32 v1, 1
	v_lshlrev_b32_e32 v1, s99, v1
	buffer_wbl2 sc1
	s_waitcnt vmcnt(0) lgkmcnt(0)
	s_load_dword s101, s[4:5], 0x28
	global_atomic_add v3, v1, s[4:5] offset:16
	s_waitcnt vmcnt(0)
	v_mov_b32_e32 v4, 0
	v_mov_b32_e32 v1, 1
	global_atomic_add v4, v1, s[4:5] offset:36
	s_waitcnt lgkmcnt(0)
	s_mov_b32 s99, s101
	s_mov_b64 s[8:9], exec
	s_mov_b64 s[6:7], 0
.Lhs_poll_1:
	global_load_dword v2, v4, s[4:5] offset:36 sc1
	s_waitcnt vmcnt(0)
	v_subrev_u32_e32 v2, s99, v2
	v_cmp_le_i32_e32 vcc, 0, v2
	s_or_b64 s[6:7], vcc, s[6:7]
	s_andn2_b64 exec, exec, s[6:7]
	s_cbranch_execz .Lhs_done_1
	s_sleep 2
	s_branch .Lhs_poll_1
.Lhs_done_1:
	s_mov_b64 exec, s[8:9]
	global_load_dword v2, v3, s[4:5] offset:16 sc1
	s_waitcnt vmcnt(0)
	s_getreg_b32 s10, hwreg(HW_REG_XCC_ID)
	s_and_b32 s10, s10, 1
	s_lshl_b32 s10, s10, 4
	v_lshrrev_b32_e32 v2, s10, v2
	v_and_b32_e32 v2, 0xffff, v2
	s_nop 1
	v_readfirstlane_b32 s98, v2
	s_mov_b32 s99, 0
	global_load_dword v1, v4, s[4:5] offset:16 sc1
	s_waitcnt vmcnt(0)
	v_readfirstlane_b32 s10, v1
	s_nop 3
	s_and_b32 s11, s10, 0xffff
	s_min_u32 s11, s11, 1
	s_add_u32 s99, s99, s11
	s_lshr_b32 s11, s10, 16
	s_min_u32 s11, s11, 1
	s_add_u32 s99, s99, s11
	global_load_dword v1, v4, s[4:5] offset:20 sc1
	s_waitcnt vmcnt(0)
	v_readfirstlane_b32 s10, v1
	s_nop 3
	s_and_b32 s11, s10, 0xffff
	s_min_u32 s11, s11, 1
	s_add_u32 s99, s99, s11
	s_lshr_b32 s11, s10, 16
	s_min_u32 s11, s11, 1
	s_add_u32 s99, s99, s11
	global_load_dword v1, v4, s[4:5] offset:24 sc1
	s_waitcnt vmcnt(0)
	v_readfirstlane_b32 s10, v1
	s_nop 3
	s_and_b32 s11, s10, 0xffff
	s_min_u32 s11, s11, 1
	s_add_u32 s99, s99, s11
	s_lshr_b32 s11, s10, 16
	s_min_u32 s11, s11, 1
	s_add_u32 s99, s99, s11
	global_load_dword v1, v4, s[4:5] offset:28 sc1
	s_waitcnt vmcnt(0)
	v_readfirstlane_b32 s10, v1
	s_nop 3
	s_and_b32 s11, s10, 0xffff
	s_min_u32 s11, s11, 1
	s_add_u32 s99, s99, s11
	s_lshr_b32 s11, s10, 16
	s_min_u32 s11, s11, 1
	s_add_u32 s99, s99, s11
	s_nop 3
	s_lshl_b32 s98, s98, 8
	s_lshl_b32 s99, s99, 16
	s_or_b32 s100, s98, s99
	buffer_inv sc1
	s_waitcnt vmcnt(0)

; #define SEAM(k) do { if (IN(k) && IN((k) + 1)) grid.sync(); if (PROBE_PH >= 0) { const unsigned long long tn_ = __builtin_amdgcn_s_memrealtime(); if ((PROBE_PH >> (k)) & 1) tp1 += tn_ - tp0; tp0 = tn_; } } while (0)
; __global__ void __launch_bounds__(512, 2) mega(Params p) {
;     ...
;     SEAM(2);
.LBB0_359:
	s_cmp_gt_i32 s67, 3
	s_cselect_b64 s[0:1], -1, 0
	s_and_b64 s[2:3], s[8:9], s[0:1]
	s_andn2_b64 vcc, exec, s[2:3]
	s_cbranch_vccnz .LBB0_371
	v_and_b32_e32 v1, 0x3fffffff, v0
	v_cmp_eq_u32_e32 vcc, 0, v1
	s_waitcnt vmcnt(0) lgkmcnt(0)
	s_barrier
	s_and_saveexec_b64 s[2:3], vcc
	s_cbranch_execz .LBB0_370
	s_load_dwordx2 s[4:5], s[68:69], 0x58
	s_getreg_b32 s101, hwreg(HW_REG_XCC_ID)
	s_and_b32 s101, s101, 7
	s_lshr_b32 s98, s101, 1
	s_lshl_b32 s98, s98, 2
	s_and_b32 s99, s101, 1
	s_lshl_b32 s99, s99, 4
	v_mov_b32_e32 v3, s98
	v_mov_b32_e32 v1, 1
	v_lshlrev_b32_e32 v1, s99, v1
	s_waitcnt vmcnt(0) lgkmcnt(0)
	global_atomic_add v2, v3, v1, s[4:5] offset:16 sc0
	s_load_dword s101, s[4:5], 0x28
	s_waitcnt vmcnt(0)
	v_lshrrev_b32_e32 v2, s99, v2
	v_and_b32_e32 v2, 0xffff, v2
	v_add_u32_e32 v2, 1, v2
	s_and_b32 s98, s100, 0xff
	s_add_u32 s98, s98, 2
	s_bfe_u32 s99, s100, 0x80008
	s_mul_i32 s98, s98, s99
	v_mov_b32_e32 v4, 0
	v_mov_b32_e32 v1, 1
	v_cmp_eq_u32_e32 vcc, s98, v2
	s_waitcnt lgkmcnt(0)
	s_and_b32 s98, s100, 0xff
	s_add_u32 s98, s98, 1
	s_bfe_u32 s99, s100, 0x80010
	s_mul_i32 s99, s99, s98
	s_add_u32 s99, s99, s101
	s_add_u32 s100, s100, 1
	s_and_saveexec_b64 s[6:7], vcc
	s_cbranch_execz .Lhs_nl_2
	buffer_wbl2 sc1
	s_waitcnt vmcnt(0)
	global_atomic_add v4, v1, s[4:5] offset:36

; #define SEAM(k) do { if (IN(k) && IN((k) + 1)) grid.sync(); if (PROBE_PH >= 0) { const unsigned long long tn_ = __builtin_amdgcn_s_memrealtime(); if ((PROBE_PH >> (k)) & 1) tp1 += tn_ - tp0; tp0 = tn_; } } while (0)
; __global__ void __launch_bounds__(512, 2) mega(Params p) {
;     ...
;     SEAM(3);
.LBB0_399:
	s_cmp_gt_i32 s67, 4
	s_cselect_b64 s[2:3], -1, 0
	s_and_b64 s[0:1], s[0:1], s[2:3]
	s_andn2_b64 vcc, exec, s[0:1]
	s_cbranch_vccnz .LBB0_411
	v_and_b32_e32 v1, 0x3fffffff, v0
	v_cmp_eq_u32_e32 vcc, 0, v1
	s_waitcnt vmcnt(0) lgkmcnt(0)
	s_barrier
	s_and_saveexec_b64 s[0:1], vcc
	s_cbranch_execz .LBB0_410
	s_load_dwordx2 s[4:5], s[68:69], 0x58
	s_getreg_b32 s101, hwreg(HW_REG_XCC_ID)
	s_and_b32 s101, s101, 7
	s_lshr_b32 s98, s101, 1
	s_lshl_b32 s98, s98, 2
	s_and_b32 s99, s101, 1
	s_lshl_b32 s99, s99, 4
	v_mov_b32_e32 v3, s98
	v_mov_b32_e32 v1, 1
	v_lshlrev_b32_e32 v1, s99, v1
	s_waitcnt vmcnt(0) lgkmcnt(0)
	global_atomic_add v2, v3, v1, s[4:5] offset:16 sc0
	s_load_dword s101, s[4:5], 0x28
	s_waitcnt vmcnt(0)
	v_lshrrev_b32_e32 v2, s99, v2
	v_and_b32_e32 v2, 0xffff, v2
	v_add_u32_e32 v2, 1, v2
	s_and_b32 s98, s100, 0xff
	s_add_u32 s98, s98, 2
	s_bfe_u32 s99, s100, 0x80008
	s_mul_i32 s98, s98, s99
	v_mov_b32_e32 v4, 0
	v_mov_b32_e32 v1, 1
	v_cmp_eq_u32_e32 vcc, s98, v2
	s_waitcnt lgkmcnt(0)
	s_and_b32 s98, s100, 0xff
	s_add_u32 s98, s98, 1
	s_bfe_u32 s99, s100, 0x80010
	s_mul_i32 s99, s99, s98
	s_add_u32 s99, s99, s101
	s_add_u32 s100, s100, 1
	s_and_saveexec_b64 s[6:7], vcc
	s_cbranch_execz .Lhs_nl_3
	buffer_wbl2 sc1
	s_waitcnt vmcnt(0)
	global_atomic_add v4, v1, s[4:5] offset:36

; #define SEAM(k) do { if (IN(k) && IN((k) + 1)) grid.sync(); if (PROBE_PH >= 0) { const unsigned long long tn_ = __builtin_amdgcn_s_memrealtime(); if ((PROBE_PH >> (k)) & 1) tp1 += tn_ - tp0; tp0 = tn_; } } while (0)
; __global__ void __launch_bounds__(512, 2) mega(Params p) {
;     ...
;     SEAM(4);
.LBB0_578:
	s_cmp_gt_i32 s67, 5
	v_readlane_b32 s2, v251, 34
	s_cselect_b64 s[0:1], -1, 0
	v_readlane_b32 s3, v251, 35
	s_and_b64 s[2:3], s[2:3], s[0:1]
	s_andn2_b64 vcc, exec, s[2:3]
	s_cbranch_vccnz .LBB0_590
	v_and_b32_e32 v1, 0x3fffffff, v0
	v_cmp_eq_u32_e32 vcc, 0, v1
	s_waitcnt vmcnt(0) lgkmcnt(0)
	s_barrier
	s_and_saveexec_b64 s[2:3], vcc
	s_cbranch_execz .LBB0_589
	s_load_dwordx2 s[4:5], s[68:69], 0x58
	s_getreg_b32 s101, hwreg(HW_REG_XCC_ID)
	s_and_b32 s101, s101, 7
	s_lshr_b32 s98, s101, 1
	s_lshl_b32 s98, s98, 2
	s_and_b32 s99, s101, 1
	s_lshl_b32 s99, s99, 4
	v_mov_b32_e32 v3, s98
	v_mov_b32_e32 v1, 1
	v_lshlrev_b32_e32 v1, s99, v1
	s_waitcnt vmcnt(0) lgkmcnt(0)
	global_atomic_add v2, v3, v1, s[4:5] offset:16 sc0
	s_load_dword s101, s[4:5], 0x28
	s_waitcnt vmcnt(0)
	v_lshrrev_b32_e32 v2, s99, v2
	v_and_b32_e32 v2, 0xffff, v2
	v_add_u32_e32 v2, 1, v2
	s_and_b32 s98, s100, 0xff
	s_add_u32 s98, s98, 2
	s_bfe_u32 s99, s100, 0x80008
	s_mul_i32 s98, s98, s99
	v_mov_b32_e32 v4, 0
	v_mov_b32_e32 v1, 1
	v_cmp_eq_u32_e32 vcc, s98, v2
	s_waitcnt lgkmcnt(0)
	s_and_b32 s98, s100, 0xff
	s_add_u32 s98, s98, 1
	s_bfe_u32 s99, s100, 0x80010
	s_mul_i32 s99, s99, s98
	s_add_u32 s99, s99, s101
	s_add_u32 s100, s100, 1
	s_and_saveexec_b64 s[6:7], vcc
	s_cbranch_execz .Lhs_nl_4
	buffer_wbl2 sc1
	s_waitcnt vmcnt(0)
	global_atomic_add v4, v1, s[4:5] offset:36

; #define SEAM(k) do { if (IN(k) && IN((k) + 1)) grid.sync(); if (PROBE_PH >= 0) { const unsigned long long tn_ = __builtin_amdgcn_s_memrealtime(); if ((PROBE_PH >> (k)) & 1) tp1 += tn_ - tp0; tp0 = tn_; } } while (0)
; __global__ void __launch_bounds__(512, 2) mega(Params p) {
;     ...
;     SEAM(5);
.LBB0_625:
	s_cmp_gt_i32 s67, 6
	s_cselect_b64 s[2:3], -1, 0
	s_and_b64 s[0:1], s[0:1], s[2:3]
	s_andn2_b64 vcc, exec, s[0:1]
	s_cbranch_vccnz .LBB0_637
	v_and_b32_e32 v1, 0x3fffffff, v0
	v_cmp_eq_u32_e32 vcc, 0, v1
	s_waitcnt vmcnt(0) lgkmcnt(0)
	s_barrier
	s_and_saveexec_b64 s[0:1], vcc
	s_cbranch_execz .LBB0_636
	s_load_dwordx2 s[4:5], s[68:69], 0x58
	s_getreg_b32 s101, hwreg(HW_REG_XCC_ID)
	s_and_b32 s101, s101, 7
	s_lshr_b32 s98, s101, 1
	s_lshl_b32 s98, s98, 2
	s_and_b32 s99, s101, 1
	s_lshl_b32 s99, s99, 4
	v_mov_b32_e32 v3, s98
	v_mov_b32_e32 v1, 1
	v_lshlrev_b32_e32 v1, s99, v1
	s_waitcnt vmcnt(0) lgkmcnt(0)
	global_atomic_add v2, v3, v1, s[4:5] offset:16 sc0
	s_load_dword s101, s[4:5], 0x28
	s_waitcnt vmcnt(0)
	v_lshrrev_b32_e32 v2, s99, v2
	v_and_b32_e32 v2, 0xffff, v2
	v_add_u32_e32 v2, 1, v2
	s_and_b32 s98, s100, 0xff
	s_add_u32 s98, s98, 2
	s_bfe_u32 s99, s100, 0x80008
	s_mul_i32 s98, s98, s99
	v_mov_b32_e32 v4, 0
	v_mov_b32_e32 v1, 1
	v_cmp_eq_u32_e32 vcc, s98, v2
	s_waitcnt lgkmcnt(0)
	s_and_b32 s98, s100, 0xff
	s_add_u32 s98, s98, 1
	s_bfe_u32 s99, s100, 0x80010
	s_mul_i32 s99, s99, s98
	s_add_u32 s99, s99, s101
	s_add_u32 s100, s100, 1
	s_and_saveexec_b64 s[6:7], vcc
	s_cbranch_execz .Lhs_nl_5
	buffer_wbl2 sc1
	s_waitcnt vmcnt(0)
	global_atomic_add v4, v1, s[4:5] offset:36

; #define SEAM(k) do { if (IN(k) && IN((k) + 1)) grid.sync(); if (PROBE_PH >= 0) { const unsigned long long tn_ = __builtin_amdgcn_s_memrealtime(); if ((PROBE_PH >> (k)) & 1) tp1 += tn_ - tp0; tp0 = tn_; } } while (0)
; __global__ void __launch_bounds__(512, 2) mega(Params p) {
;     ...
;     SEAM(6);
.LBB0_658:
	v_readlane_b32 s2, v251, 32
	v_readlane_b32 s3, v251, 33
	s_waitcnt lgkmcnt(0)
	s_load_dwordx16 s[4:19], s[2:3], 0x110
	s_cmp_gt_i32 s67, 7
	s_cselect_b64 s[2:3], -1, 0
	s_and_b64 s[0:1], s[0:1], s[2:3]
	s_andn2_b64 vcc, exec, s[0:1]
	s_waitcnt lgkmcnt(0)
	v_writelane_b32 v250, s4, 5
	s_nop 1
	v_writelane_b32 v250, s5, 6
	v_writelane_b32 v250, s6, 7
	v_writelane_b32 v250, s7, 8
	v_writelane_b32 v250, s8, 9
	v_writelane_b32 v250, s9, 10
	v_writelane_b32 v250, s10, 11
	v_writelane_b32 v250, s11, 12
	v_writelane_b32 v250, s12, 13
	v_writelane_b32 v250, s13, 14
	v_writelane_b32 v250, s14, 15
	v_writelane_b32 v250, s15, 16
	v_writelane_b32 v250, s16, 17
	v_writelane_b32 v250, s17, 18
	v_writelane_b32 v250, s18, 19
	v_writelane_b32 v250, s19, 20
	s_cbranch_vccnz .LBB0_670
	v_and_b32_e32 v1, 0x3fffffff, v0
	v_cmp_eq_u32_e32 vcc, 0, v1
	s_waitcnt vmcnt(0)
	s_barrier
	s_and_saveexec_b64 s[0:1], vcc
	s_cbranch_execz .LBB0_669
	s_load_dwordx2 s[4:5], s[68:69], 0x58
	s_getreg_b32 s101, hwreg(HW_REG_XCC_ID)
	s_and_b32 s101, s101, 7
	s_lshr_b32 s98, s101, 1
	s_lshl_b32 s98, s98, 2
	s_and_b32 s99, s101, 1
	s_lshl_b32 s99, s99, 4
	v_mov_b32_e32 v3, s98
	v_mov_b32_e32 v1, 1
	v_lshlrev_b32_e32 v1, s99, v1
	s_waitcnt vmcnt(0) lgkmcnt(0)
	global_atomic_add v2, v3, v1, s[4:5] offset:16 sc0
	s_load_dword s101, s[4:5], 0x28
	s_waitcnt vmcnt(0)
	v_lshrrev_b32_e32 v2, s99, v2
	v_and_b32_e32 v2, 0xffff, v2
	v_add_u32_e32 v2, 1, v2
	s_and_b32 s98, s100, 0xff
	s_add_u32 s98, s98, 2
	s_bfe_u32 s99, s100, 0x80008
	s_mul_i32 s98, s98, s99
	v_mov_b32_e32 v4, 0
	v_mov_b32_e32 v1, 1
	v_cmp_eq_u32_e32 vcc, s98, v2
	s_waitcnt lgkmcnt(0)
	s_and_b32 s98, s100, 0xff
	s_add_u32 s98, s98, 1
	s_bfe_u32 s99, s100, 0x80010
	s_mul_i32 s99, s99, s98
	s_add_u32 s99, s99, s101
	s_add_u32 s100, s100, 1
	s_and_saveexec_b64 s[6:7], vcc
	s_cbranch_execz .Lhs_nl_6
	buffer_wbl2 sc1
	s_waitcnt vmcnt(0)
	global_atomic_add v4, v1, s[4:5] offset:36

; #define SEAM(k) do { if (IN(k) && IN((k) + 1)) grid.sync(); if (PROBE_PH >= 0) { const unsigned long long tn_ = __builtin_amdgcn_s_memrealtime(); if ((PROBE_PH >> (k)) & 1) tp1 += tn_ - tp0; tp0 = tn_; } } while (0)
; __global__ void __launch_bounds__(512, 2) mega(Params p) {
;     ...
;     SEAM(7);
.LBB0_699:
	s_cmp_gt_i32 s67, 8
	s_cselect_b64 s[2:3], -1, 0
	s_and_b64 s[0:1], s[0:1], s[2:3]
	s_andn2_b64 vcc, exec, s[0:1]
	s_cbranch_vccnz .LBB0_711
	v_and_b32_e32 v1, 0x3fffffff, v0
	v_cmp_eq_u32_e32 vcc, 0, v1
	s_barrier
	s_and_saveexec_b64 s[0:1], vcc
	s_cbranch_execz .LBB0_710
	s_load_dwordx2 s[4:5], s[68:69], 0x58
	s_getreg_b32 s101, hwreg(HW_REG_XCC_ID)
	s_and_b32 s101, s101, 7
	s_lshr_b32 s98, s101, 1
	s_lshl_b32 s98, s98, 2
	s_and_b32 s99, s101, 1
	s_lshl_b32 s99, s99, 4
	v_mov_b32_e32 v3, s98
	v_mov_b32_e32 v1, 1
	v_lshlrev_b32_e32 v1, s99, v1
	s_waitcnt vmcnt(0) lgkmcnt(0)
	global_atomic_add v2, v3, v1, s[4:5] offset:16 sc0
	s_load_dword s101, s[4:5], 0x28
	s_waitcnt vmcnt(0)
	v_lshrrev_b32_e32 v2, s99, v2
	v_and_b32_e32 v2, 0xffff, v2
	v_add_u32_e32 v2, 1, v2
	s_and_b32 s98, s100, 0xff
	s_add_u32 s98, s98, 2
	s_bfe_u32 s99, s100, 0x80008
	s_mul_i32 s98, s98, s99
	v_mov_b32_e32 v4, 0
	v_mov_b32_e32 v1, 1
	v_cmp_eq_u32_e32 vcc, s98, v2
	s_waitcnt lgkmcnt(0)
	s_and_b32 s98, s100, 0xff
	s_add_u32 s98, s98, 1
	s_bfe_u32 s99, s100, 0x80010
	s_mul_i32 s99, s99, s98
	s_add_u32 s99, s99, s101
	s_add_u32 s100, s100, 1
	s_and_saveexec_b64 s[6:7], vcc
	s_cbranch_execz .Lhs_nl_7
	buffer_wbl2 sc1
	s_waitcnt vmcnt(0)
	global_atomic_add v4, v1, s[4:5] offset:36

; #define SEAM(k) do { if (IN(k) && IN((k) + 1)) grid.sync(); if (PROBE_PH >= 0) { const unsigned long long tn_ = __builtin_amdgcn_s_memrealtime(); if ((PROBE_PH >> (k)) & 1) tp1 += tn_ - tp0; tp0 = tn_; } } while (0)
; __global__ void __launch_bounds__(512, 2) mega(Params p) {
;     ...
;     SEAM(8);
.LBB0_814:
	s_cmp_gt_i32 s67, 9
	s_cselect_b64 s[0:1], -1, 0
	s_and_b64 s[2:3], s[6:7], s[0:1]
	s_andn2_b64 vcc, exec, s[2:3]
	s_cbranch_vccnz .LBB0_826
	v_and_b32_e32 v1, 0x3fffffff, v0
	v_cmp_eq_u32_e32 vcc, 0, v1
	s_waitcnt vmcnt(0) lgkmcnt(0)
	s_barrier
	s_and_saveexec_b64 s[2:3], vcc
	s_cbranch_execz .LBB0_825
	s_load_dwordx2 s[4:5], s[68:69], 0x58
	s_getreg_b32 s101, hwreg(HW_REG_XCC_ID)
	s_and_b32 s101, s101, 7
	s_lshr_b32 s98, s101, 1
	s_lshl_b32 s98, s98, 2
	s_and_b32 s99, s101, 1
	s_lshl_b32 s99, s99, 4
	v_mov_b32_e32 v3, s98
	v_mov_b32_e32 v1, 1
	v_lshlrev_b32_e32 v1, s99, v1
	s_waitcnt vmcnt(0) lgkmcnt(0)
	global_atomic_add v2, v3, v1, s[4:5] offset:16 sc0
	s_load_dword s101, s[4:5], 0x28
	s_waitcnt vmcnt(0)
	v_lshrrev_b32_e32 v2, s99, v2
	v_and_b32_e32 v2, 0xffff, v2
	v_add_u32_e32 v2, 1, v2
	s_and_b32 s98, s100, 0xff
	s_add_u32 s98, s98, 2
	s_bfe_u32 s99, s100, 0x80008
	s_mul_i32 s98, s98, s99
	v_mov_b32_e32 v4, 0
	v_mov_b32_e32 v1, 1
	v_cmp_eq_u32_e32 vcc, s98, v2
	s_waitcnt lgkmcnt(0)
	s_and_b32 s98, s100, 0xff
	s_add_u32 s98, s98, 1
	s_bfe_u32 s99, s100, 0x80010
	s_mul_i32 s99, s99, s98
	s_add_u32 s99, s99, s101
	s_add_u32 s100, s100, 1
	s_and_saveexec_b64 s[6:7], vcc
	s_cbranch_execz .Lhs_nl_8
	buffer_wbl2 sc1
	s_waitcnt vmcnt(0)
	global_atomic_add v4, v1, s[4:5] offset:36

; __global__ void __launch_bounds__(512, 2) mega(Params p) {
;     ...
;         grid.sync();
.LBB0_832:
	s_or_b64 exec, exec, s[0:1]
	v_lshrrev_b32_e32 v1, 20, v0
	v_lshrrev_b32_e32 v2, 10, v0
	v_or_b32_e32 v1, v2, v1
	s_movk_i32 s0, 0x3ff
	v_and_or_b32 v1, v1, s0, v103
	v_cmp_eq_u32_e32 vcc, 0, v1
	s_waitcnt lgkmcnt(0)
	s_barrier
	s_and_saveexec_b64 s[0:1], vcc
	s_cbranch_execz .LBB0_842
	s_load_dwordx2 s[2:3], s[68:69], 0x58
	s_getreg_b32 s101, hwreg(HW_REG_XCC_ID)
	s_and_b32 s101, s101, 7
	s_lshr_b32 s98, s101, 1
	s_lshl_b32 s98, s98, 2
	s_and_b32 s99, s101, 1
	s_lshl_b32 s99, s99, 4
	v_mov_b32_e32 v3, s98
	v_mov_b32_e32 v1, 1
	v_lshlrev_b32_e32 v1, s99, v1
	s_waitcnt vmcnt(0) lgkmcnt(0)
	global_atomic_add v2, v3, v1, s[2:3] offset:16 sc0
	s_load_dword s101, s[2:3], 0x28
	s_waitcnt vmcnt(0)
	v_lshrrev_b32_e32 v2, s99, v2
	v_and_b32_e32 v2, 0xffff, v2
	v_add_u32_e32 v2, 1, v2
	s_and_b32 s98, s100, 0xff
	s_add_u32 s98, s98, 2
	s_bfe_u32 s99, s100, 0x80008
	s_mul_i32 s98, s98, s99
	v_mov_b32_e32 v4, 0
	v_mov_b32_e32 v1, 1
	v_cmp_eq_u32_e32 vcc, s98, v2
	s_waitcnt lgkmcnt(0)
	s_and_b32 s98, s100, 0xff
	s_add_u32 s98, s98, 1
	s_bfe_u32 s99, s100, 0x80010
	s_mul_i32 s99, s99, s98
	s_add_u32 s99, s99, s101
	s_add_u32 s100, s100, 1
	s_and_saveexec_b64 s[4:5], vcc
	s_cbranch_execz .Lhs_nl_9
	buffer_wbl2 sc1
	s_waitcnt vmcnt(0)
	global_atomic_add v4, v1, s[2:3] offset:36

; __global__ void __launch_bounds__(512, 2) mega(Params p) {
;     ...
;         grid.sync();
.Lhs_poll_9:
	global_load_dword v2, v4, s[2:3] offset:36 sc1
	s_waitcnt vmcnt(0)
	v_subrev_u32_e32 v2, s99, v2
	v_cmp_le_i32_e32 vcc, 0, v2
	s_or_b64 s[4:5], vcc, s[4:5]
	s_andn2_b64 exec, exec, s[4:5]
	s_cbranch_execz .Lhs_done_9
	s_sleep 2
	s_branch .Lhs_poll_9

; #define SEAM(k) do { if (IN(k) && IN((k) + 1)) grid.sync(); if (PROBE_PH >= 0) { const unsigned long long tn_ = __builtin_amdgcn_s_memrealtime(); if ((PROBE_PH >> (k)) & 1) tp1 += tn_ - tp0; tp0 = tn_; } } while (0)
; __global__ void __launch_bounds__(512, 2) mega(Params p) {
;     ...
;     SEAM(9);
.LBB0_1028:
	s_cmp_gt_i32 s67, 10
	v_readlane_b32 s2, v250, 45
	s_cselect_b64 s[0:1], -1, 0
	v_readlane_b32 s3, v250, 46
	s_and_b64 s[2:3], s[2:3], s[0:1]
	s_andn2_b64 vcc, exec, s[2:3]
	s_cbranch_vccnz .LBB0_1040
	v_and_b32_e32 v1, 0x3fffffff, v0
	v_cmp_eq_u32_e32 vcc, 0, v1
	s_waitcnt vmcnt(0) lgkmcnt(0)
	s_barrier
	s_and_saveexec_b64 s[2:3], vcc
	s_cbranch_execz .LBB0_1039
	s_load_dwordx2 s[4:5], s[68:69], 0x58
	s_getreg_b32 s101, hwreg(HW_REG_XCC_ID)
	s_and_b32 s101, s101, 7
	s_lshr_b32 s98, s101, 1
	s_lshl_b32 s98, s98, 2
	s_and_b32 s99, s101, 1
	s_lshl_b32 s99, s99, 4
	v_mov_b32_e32 v3, s98
	v_mov_b32_e32 v1, 1
	v_lshlrev_b32_e32 v1, s99, v1
	s_waitcnt vmcnt(0) lgkmcnt(0)
	global_atomic_add v2, v3, v1, s[4:5] offset:16 sc0
	s_load_dword s101, s[4:5], 0x28
	s_waitcnt vmcnt(0)
	v_lshrrev_b32_e32 v2, s99, v2
	v_and_b32_e32 v2, 0xffff, v2
	v_add_u32_e32 v2, 1, v2
	s_and_b32 s98, s100, 0xff
	s_add_u32 s98, s98, 2
	s_bfe_u32 s99, s100, 0x80008
	s_mul_i32 s98, s98, s99
	v_mov_b32_e32 v4, 0
	v_mov_b32_e32 v1, 1
	v_cmp_eq_u32_e32 vcc, s98, v2
	s_waitcnt lgkmcnt(0)
	s_and_b32 s98, s100, 0xff
	s_add_u32 s98, s98, 1
	s_bfe_u32 s99, s100, 0x80010
	s_mul_i32 s99, s99, s98
	s_add_u32 s99, s99, s101
	s_add_u32 s100, s100, 1
	s_and_saveexec_b64 s[6:7], vcc
	s_cbranch_execz .Lhs_nl_10
	buffer_wbl2 sc1
	s_waitcnt vmcnt(0)
	global_atomic_add v4, v1, s[4:5] offset:36

; #define SEAM(k) do { if (IN(k) && IN((k) + 1)) grid.sync(); if (PROBE_PH >= 0) { const unsigned long long tn_ = __builtin_amdgcn_s_memrealtime(); if ((PROBE_PH >> (k)) & 1) tp1 += tn_ - tp0; tp0 = tn_; } } while (0)
; __global__ void __launch_bounds__(512, 2) mega(Params p) {
;     ...
;     SEAM(10);
.LBB0_1061:
	s_cmp_gt_i32 s67, 11
	s_cselect_b64 s[0:1], -1, 0
	s_and_b64 s[2:3], s[8:9], s[0:1]
	s_andn2_b64 vcc, exec, s[2:3]
	s_cbranch_vccnz .LBB0_1073
	v_and_b32_e32 v1, 0x3fffffff, v0
	v_cmp_eq_u32_e32 vcc, 0, v1
	s_waitcnt vmcnt(0) lgkmcnt(0)
	s_barrier
	s_and_saveexec_b64 s[2:3], vcc
	s_cbranch_execz .LBB0_1072
	s_load_dwordx2 s[4:5], s[68:69], 0x58
	s_getreg_b32 s101, hwreg(HW_REG_XCC_ID)
	s_and_b32 s101, s101, 7
	s_lshr_b32 s98, s101, 1
	s_lshl_b32 s98, s98, 2
	s_and_b32 s99, s101, 1
	s_lshl_b32 s99, s99, 4
	v_mov_b32_e32 v3, s98
	v_mov_b32_e32 v1, 1
	v_lshlrev_b32_e32 v1, s99, v1
	s_waitcnt vmcnt(0) lgkmcnt(0)
	global_atomic_add v2, v3, v1, s[4:5] offset:16 sc0
	s_load_dword s101, s[4:5], 0x28
	s_waitcnt vmcnt(0)
	v_lshrrev_b32_e32 v2, s99, v2
	v_and_b32_e32 v2, 0xffff, v2
	v_add_u32_e32 v2, 1, v2
	s_and_b32 s98, s100, 0xff
	s_add_u32 s98, s98, 2
	s_bfe_u32 s99, s100, 0x80008
	s_mul_i32 s98, s98, s99
	v_mov_b32_e32 v4, 0
	v_mov_b32_e32 v1, 1
	v_cmp_eq_u32_e32 vcc, s98, v2
	s_waitcnt lgkmcnt(0)
	s_and_b32 s98, s100, 0xff
	s_add_u32 s98, s98, 1
	s_bfe_u32 s99, s100, 0x80010
	s_mul_i32 s99, s99, s98
	s_add_u32 s99, s99, s101
	s_add_u32 s100, s100, 1
	s_and_saveexec_b64 s[6:7], vcc
	s_cbranch_execz .Lhs_nl_11
	buffer_wbl2 sc1
	s_waitcnt vmcnt(0)
	global_atomic_add v4, v1, s[4:5] offset:36

; #define SEAM(k) do { if (IN(k) && IN((k) + 1)) grid.sync(); if (PROBE_PH >= 0) { const unsigned long long tn_ = __builtin_amdgcn_s_memrealtime(); if ((PROBE_PH >> (k)) & 1) tp1 += tn_ - tp0; tp0 = tn_; } } while (0)
; __global__ void __launch_bounds__(512, 2) mega(Params p) {
;     ...
;     SEAM(11);
.LBB0_1094:
	s_cmp_gt_i32 s67, 12
	s_cselect_b64 s[0:1], -1, 0
	s_and_b64 s[2:3], s[2:3], s[0:1]
	s_andn2_b64 vcc, exec, s[2:3]
	s_cbranch_vccnz .LBB0_1106
	v_and_b32_e32 v1, 0x3fffffff, v0
	v_cmp_eq_u32_e32 vcc, 0, v1
	s_waitcnt vmcnt(0) lgkmcnt(0)
	s_barrier
	s_and_saveexec_b64 s[2:3], vcc
	s_cbranch_execz .LBB0_1105
	s_load_dwordx2 s[4:5], s[68:69], 0x58
	s_getreg_b32 s101, hwreg(HW_REG_XCC_ID)
	s_and_b32 s101, s101, 7
	s_lshr_b32 s98, s101, 1
	s_lshl_b32 s98, s98, 2
	s_and_b32 s99, s101, 1
	s_lshl_b32 s99, s99, 4
	v_mov_b32_e32 v3, s98
	v_mov_b32_e32 v1, 1
	v_lshlrev_b32_e32 v1, s99, v1
	s_waitcnt vmcnt(0) lgkmcnt(0)
	global_atomic_add v2, v3, v1, s[4:5] offset:16 sc0
	s_load_dword s101, s[4:5], 0x28
	s_waitcnt vmcnt(0)
	v_lshrrev_b32_e32 v2, s99, v2
	v_and_b32_e32 v2, 0xffff, v2
	v_add_u32_e32 v2, 1, v2
	s_and_b32 s98, s100, 0xff
	s_add_u32 s98, s98, 2
	s_bfe_u32 s99, s100, 0x80008
	s_mul_i32 s98, s98, s99
	v_mov_b32_e32 v4, 0
	v_mov_b32_e32 v1, 1
	v_cmp_eq_u32_e32 vcc, s98, v2
	s_waitcnt lgkmcnt(0)
	s_and_b32 s98, s100, 0xff
	s_add_u32 s98, s98, 1
	s_bfe_u32 s99, s100, 0x80010
	s_mul_i32 s99, s99, s98
	s_add_u32 s99, s99, s101
	s_add_u32 s100, s100, 1
	s_and_saveexec_b64 s[6:7], vcc
	s_cbranch_execz .Lhs_nl_12
	buffer_wbl2 sc1
	s_waitcnt vmcnt(0)
	global_atomic_add v4, v1, s[4:5] offset:36
